# v22 + nt cache hints on once-read x / mem / f32-weight loads and on final LayerNorm output stores
# speedup vs baseline: 1.0014x; 1.0014x over previous
; __device__ __forceinline__ unsigned pk2(float lo, float hi) { return f2bf(lo) | (f2bf(hi) << 16); }
; __global__ void __launch_bounds__(NWAVES * 64, 2) mega_fwd(Params P) {
;     ...
;                 for (size_t i = gt; i < (size_t)TOK * DM / 4; i += (size_t)NGT * 8) { f32x4 v[8];
; #pragma unroll
;                     for (int j = 0; j < 8; ++j) v[j] = ((const f32x4*)x)[i + (size_t)j * NGT];
; #pragma unroll
;                     for (int j = 0; j < 8; ++j) { u32x2 w; w.x = pk2(v[j][0], v[j][1]); w.y = pk2(v[j][2], v[j][3]); ((u32x2*)XBB)[i + (size_t)j * NGT] = w; } }
.LBB0_20:
	v_add_co_u32_e32 v16, vcc, 0x200000, v14
	s_mov_b64 s[4:5], vcc
	v_add_co_u32_e32 v44, vcc, s42, v12
	global_load_dwordx4 v[2:5], v[14:15], off nt
	s_nop 0
	v_addc_co_u32_e32 v45, vcc, 0, v13, vcc
	v_add_co_u32_e32 v46, vcc, s22, v12
	v_lshl_add_u64 v[10:11], v[10:11], 0, s[12:13]
	s_nop 0
	v_addc_co_u32_e32 v47, vcc, 0, v13, vcc
	v_add_co_u32_e32 v48, vcc, s43, v12
	s_mov_b64 s[0:1], 0xefffff
	s_nop 0
	v_addc_co_u32_e32 v49, vcc, 0, v13, vcc
	v_add_co_u32_e32 v50, vcc, s28, v12
	v_cmp_lt_u64_e64 s[38:39], s[0:1], v[10:11]
	s_nop 0
	v_addc_co_u32_e32 v51, vcc, 0, v13, vcc
	v_add_co_u32_e32 v52, vcc, s8, v12
	s_mov_b64 s[0:1], 0x800000
	s_nop 0
	v_addc_co_u32_e32 v53, vcc, 0, v13, vcc
	v_add_co_u32_e32 v54, vcc, s33, v12
	s_or_b64 s[6:7], s[38:39], s[6:7]
	s_nop 0
	v_addc_co_u32_e32 v55, vcc, 0, v13, vcc
	v_add_co_u32_e32 v20, vcc, 0x400000, v14
	s_mov_b64 s[36:37], vcc
	v_addc_co_u32_e64 v17, vcc, 0, v15, s[4:5]
	v_add_co_u32_e32 v24, vcc, 0x600000, v14
	s_mov_b64 s[4:5], vcc
	v_addc_co_u32_e64 v21, vcc, 0, v15, s[36:37]
	v_add_co_u32_e32 v28, vcc, s21, v14
	s_mov_b64 s[36:37], vcc
	v_addc_co_u32_e64 v25, vcc, 0, v15, s[4:5]
	v_add_co_u32_e32 v32, vcc, 0xa00000, v14
	global_load_dwordx4 v[16:19], v[16:17], off nt
	s_mov_b64 s[4:5], vcc
	v_addc_co_u32_e64 v29, vcc, 0, v15, s[36:37]
	global_load_dwordx4 v[20:23], v[20:21], off nt
	v_add_co_u32_e32 v36, vcc, 0xc00000, v14
	global_load_dwordx4 v[24:27], v[24:25], off nt
	s_mov_b64 s[36:37], vcc
	v_addc_co_u32_e64 v33, vcc, 0, v15, s[4:5]
	global_load_dwordx4 v[28:31], v[28:29], off nt
	v_add_co_u32_e32 v40, vcc, 0xe00000, v14
	global_load_dwordx4 v[32:35], v[32:33], off nt
	s_mov_b64 s[4:5], vcc
	v_addc_co_u32_e64 v37, vcc, 0, v15, s[36:37]
	global_load_dwordx4 v[36:39], v[36:37], off nt
	v_addc_co_u32_e64 v41, s[4:5], 0, v15, s[4:5]
	global_load_dwordx4 v[40:43], v[40:41], off nt
	v_add_co_u32_e32 v56, vcc, 0x700000, v12
	v_lshl_add_u64 v[14:15], v[14:15], 0, s[14:15]
	s_nop 0
	v_addc_co_u32_e32 v57, vcc, 0, v13, vcc
	s_waitcnt vmcnt(7)
	v_bfe_u32 v58, v2, 16, 1
	v_bfe_u32 v60, v4, 16, 1
	v_bfe_u32 v59, v3, 16, 1
	v_bfe_u32 v61, v5, 16, 1
	v_add3_u32 v2, v2, v58, s11
	v_add3_u32 v4, v4, v60, s11
	v_add3_u32 v3, v3, v59, s11
	v_add3_u32 v5, v5, v61, s11
	v_lshrrev_b32_e32 v2, 16, v2
	v_lshrrev_b32_e32 v4, 16, v4
	v_and_or_b32 v2, v3, s23, v2
	v_and_or_b32 v3, v5, s23, v4
	global_store_dwordx2 v[12:13], v[2:3], off
	v_lshl_add_u64 v[12:13], v[12:13], 0, s[0:1]
	s_waitcnt vmcnt(7)
	v_bfe_u32 v58, v16, 16, 1
	v_bfe_u32 v60, v18, 16, 1
	v_bfe_u32 v59, v17, 16, 1
	v_bfe_u32 v61, v19, 16, 1
	v_add3_u32 v4, v16, v58, s11
	v_add3_u32 v16, v18, v60, s11
	s_waitcnt vmcnt(6)
	v_bfe_u32 v18, v20, 16, 1
	v_bfe_u32 v58, v22, 16, 1
	v_add3_u32 v5, v17, v59, s11
	v_add3_u32 v17, v19, v61, s11
	v_bfe_u32 v19, v21, 16, 1
	v_bfe_u32 v59, v23, 16, 1
	v_lshrrev_b32_e32 v2, 16, v4
	v_lshrrev_b32_e32 v3, 16, v16
	v_add3_u32 v4, v20, v18, s11
	v_add3_u32 v18, v22, v58, s11
	s_waitcnt vmcnt(5)
	v_bfe_u32 v20, v24, 16, 1
	v_bfe_u32 v22, v26, 16, 1
	v_add3_u32 v16, v21, v19, s11
	v_add3_u32 v19, v23, v59, s11
	v_bfe_u32 v21, v25, 16, 1
	v_bfe_u32 v23, v27, 16, 1
	v_and_or_b32 v2, v5, s23, v2
	v_and_or_b32 v3, v17, s23, v3
	v_lshrrev_b32_e32 v4, 16, v4
	v_lshrrev_b32_e32 v5, 16, v18
	v_add3_u32 v17, v24, v20, s11
	v_add3_u32 v20, v26, v22, s11
	s_waitcnt vmcnt(4)
	v_bfe_u32 v22, v28, 16, 1
	v_bfe_u32 v24, v30, 16, 1
	v_add3_u32 v18, v25, v21, s11
	v_add3_u32 v21, v27, v23, s11
	v_bfe_u32 v23, v29, 16, 1
	v_bfe_u32 v25, v31, 16, 1
	global_store_dwordx2 v[44:45], v[2:3], off
	v_and_or_b32 v2, v16, s23, v4
	v_and_or_b32 v3, v19, s23, v5
	v_lshrrev_b32_e32 v4, 16, v17
	v_lshrrev_b32_e32 v5, 16, v20
	v_add3_u32 v16, v28, v22, s11
	v_add3_u32 v19, v30, v24, s11
	s_waitcnt vmcnt(4)
	v_bfe_u32 v22, v32, 16, 1
	v_bfe_u32 v24, v34, 16, 1
	v_add3_u32 v17, v29, v23, s11
	v_add3_u32 v20, v31, v25, s11
	v_bfe_u32 v23, v33, 16, 1
	v_bfe_u32 v25, v35, 16, 1
	global_store_dwordx2 v[46:47], v[2:3], off
	v_and_or_b32 v2, v18, s23, v4
	v_and_or_b32 v3, v21, s23, v5
	v_lshrrev_b32_e32 v4, 16, v16
	v_lshrrev_b32_e32 v5, 16, v19
	v_add3_u32 v16, v32, v22, s11
	v_add3_u32 v19, v34, v24, s11
	s_waitcnt vmcnt(4)
	v_bfe_u32 v22, v36, 16, 1
	v_bfe_u32 v24, v38, 16, 1
	v_add3_u32 v18, v33, v23, s11
	v_add3_u32 v21, v35, v25, s11
	v_bfe_u32 v23, v37, 16, 1
	v_bfe_u32 v25, v39, 16, 1
	global_store_dwordx2 v[48:49], v[2:3], off
	v_and_or_b32 v2, v17, s23, v4
	v_and_or_b32 v3, v20, s23, v5
	v_lshrrev_b32_e32 v4, 16, v16
	v_lshrrev_b32_e32 v5, 16, v19
	v_add3_u32 v16, v36, v22, s11
	v_add3_u32 v19, v38, v24, s11
	s_waitcnt vmcnt(4)
	v_bfe_u32 v22, v40, 16, 1
	v_bfe_u32 v24, v42, 16, 1
	v_add3_u32 v17, v37, v23, s11
	v_add3_u32 v20, v39, v25, s11
	v_bfe_u32 v23, v41, 16, 1
	v_bfe_u32 v25, v43, 16, 1
	global_store_dwordx2 v[50:51], v[2:3], off
	v_and_or_b32 v2, v18, s23, v4
	v_and_or_b32 v3, v21, s23, v5
	v_lshrrev_b32_e32 v4, 16, v16
	v_lshrrev_b32_e32 v5, 16, v19
	v_add3_u32 v16, v40, v22, s11
	v_add3_u32 v19, v42, v24, s11
	v_add3_u32 v18, v41, v23, s11
	v_add3_u32 v21, v43, v25, s11
	global_store_dwordx2 v[52:53], v[2:3], off
	v_and_or_b32 v2, v17, s23, v4
	v_and_or_b32 v3, v20, s23, v5
	v_lshrrev_b32_e32 v4, 16, v16
	v_lshrrev_b32_e32 v5, 16, v19
	global_store_dwordx2 v[54:55], v[2:3], off
	v_and_or_b32 v2, v18, s23, v4
	v_and_or_b32 v3, v21, s23, v5
	global_store_dwordx2 v[56:57], v[2:3], off
	s_andn2_b64 exec, exec, s[6:7]
	s_cbranch_execnz .LBB0_20

; __device__ __forceinline__ unsigned pk2(float lo, float hi) { return f2bf(lo) | (f2bf(hi) << 16); }
; __global__ void __launch_bounds__(NWAVES * 64, 2) mega_fwd(Params P) {
;     ...
;                 for (size_t i = gt; i < (size_t)MEMT * DM / 4; i += (size_t)NGT * 8) { f32x4 v[8];
; #pragma unroll
;                     for (int j = 0; j < 8; ++j) v[j] = ((const f32x4*)mem)[i + (size_t)j * NGT];
; #pragma unroll
;                     for (int j = 0; j < 8; ++j) { u32x2 w; w.x = pk2(v[j][0], v[j][1]); w.y = pk2(v[j][2], v[j][3]); ((u32x2*)MEMB)[i + (size_t)j * NGT] = w; } }
.LBB0_23:
	v_add_co_u32_e32 v14, vcc, 0x200000, v12
	s_mov_b64 s[4:5], vcc
	v_add_co_u32_e32 v42, vcc, s42, v10
	global_load_dwordx4 v[2:5], v[12:13], off nt
	s_nop 0
	v_addc_co_u32_e32 v43, vcc, 0, v11, vcc
	v_add_co_u32_e32 v44, vcc, s22, v10
	v_lshl_add_u64 v[16:17], v[8:9], 0, s[12:13]
	s_nop 0
	v_addc_co_u32_e32 v45, vcc, 0, v11, vcc
	v_add_co_u32_e32 v46, vcc, s43, v10
	v_cmp_ge_u64_e64 s[38:39], v[16:17], v[8:9]
	s_nop 0
	v_addc_co_u32_e32 v47, vcc, 0, v11, vcc
	v_add_co_u32_e32 v48, vcc, s28, v10
	v_mov_b64_e32 v[8:9], v[16:17]
	s_nop 0
	v_addc_co_u32_e32 v49, vcc, 0, v11, vcc
	v_add_co_u32_e32 v50, vcc, s8, v10
	s_mov_b64 s[0:1], 0x800000
	s_nop 0
	v_addc_co_u32_e32 v51, vcc, 0, v11, vcc
	v_add_co_u32_e32 v52, vcc, s33, v10
	s_or_b64 s[6:7], s[38:39], s[6:7]
	s_nop 0
	v_addc_co_u32_e32 v53, vcc, 0, v11, vcc
	v_add_co_u32_e32 v18, vcc, 0x400000, v12
	s_mov_b64 s[36:37], vcc
	v_addc_co_u32_e64 v15, vcc, 0, v13, s[4:5]
	v_add_co_u32_e32 v22, vcc, 0x600000, v12
	s_mov_b64 s[4:5], vcc
	v_addc_co_u32_e64 v19, vcc, 0, v13, s[36:37]
	v_add_co_u32_e32 v26, vcc, s21, v12
	s_mov_b64 s[36:37], vcc
	v_addc_co_u32_e64 v23, vcc, 0, v13, s[4:5]
	v_add_co_u32_e32 v30, vcc, 0xa00000, v12
	global_load_dwordx4 v[14:17], v[14:15], off nt
	s_mov_b64 s[4:5], vcc
	v_addc_co_u32_e64 v27, vcc, 0, v13, s[36:37]
	global_load_dwordx4 v[18:21], v[18:19], off nt
	v_add_co_u32_e32 v34, vcc, 0xc00000, v12
	global_load_dwordx4 v[22:25], v[22:23], off nt
	s_mov_b64 s[36:37], vcc
	v_addc_co_u32_e64 v31, vcc, 0, v13, s[4:5]
	global_load_dwordx4 v[26:29], v[26:27], off nt
	v_add_co_u32_e32 v38, vcc, 0xe00000, v12
	global_load_dwordx4 v[30:33], v[30:31], off nt
	s_mov_b64 s[4:5], vcc
	v_addc_co_u32_e64 v35, vcc, 0, v13, s[36:37]
	global_load_dwordx4 v[34:37], v[34:35], off nt
	v_addc_co_u32_e64 v39, s[4:5], 0, v13, s[4:5]
	global_load_dwordx4 v[38:41], v[38:39], off nt
	v_add_co_u32_e32 v54, vcc, 0x700000, v10
	v_lshl_add_u64 v[12:13], v[12:13], 0, s[14:15]
	s_nop 0
	v_addc_co_u32_e32 v55, vcc, 0, v11, vcc
	s_waitcnt vmcnt(7)
	v_bfe_u32 v56, v2, 16, 1
	v_bfe_u32 v58, v4, 16, 1
	v_bfe_u32 v57, v3, 16, 1
	v_bfe_u32 v59, v5, 16, 1
	v_add3_u32 v2, v2, v56, s11
	v_add3_u32 v4, v4, v58, s11
	v_add3_u32 v3, v3, v57, s11
	v_add3_u32 v5, v5, v59, s11
	v_lshrrev_b32_e32 v2, 16, v2
	v_lshrrev_b32_e32 v4, 16, v4
	v_and_or_b32 v2, v3, s23, v2
	v_and_or_b32 v3, v5, s23, v4
	global_store_dwordx2 v[10:11], v[2:3], off
	v_lshl_add_u64 v[10:11], v[10:11], 0, s[0:1]
	s_waitcnt vmcnt(7)
	v_bfe_u32 v56, v14, 16, 1
	v_bfe_u32 v58, v16, 16, 1
	v_bfe_u32 v57, v15, 16, 1
	v_bfe_u32 v59, v17, 16, 1
	v_add3_u32 v4, v14, v56, s11
	v_add3_u32 v14, v16, v58, s11
	s_waitcnt vmcnt(6)
	v_bfe_u32 v16, v18, 16, 1
	v_bfe_u32 v56, v20, 16, 1
	v_add3_u32 v5, v15, v57, s11
	v_add3_u32 v15, v17, v59, s11
	v_bfe_u32 v17, v19, 16, 1
	v_bfe_u32 v57, v21, 16, 1
	v_lshrrev_b32_e32 v2, 16, v4
	v_lshrrev_b32_e32 v3, 16, v14
	v_add3_u32 v4, v18, v16, s11
	v_add3_u32 v16, v20, v56, s11
	s_waitcnt vmcnt(5)
	v_bfe_u32 v18, v22, 16, 1
	v_bfe_u32 v20, v24, 16, 1
	v_add3_u32 v14, v19, v17, s11
	v_add3_u32 v17, v21, v57, s11
	v_bfe_u32 v19, v23, 16, 1
	v_bfe_u32 v21, v25, 16, 1
	v_and_or_b32 v2, v5, s23, v2
	v_and_or_b32 v3, v15, s23, v3
	v_lshrrev_b32_e32 v4, 16, v4
	v_lshrrev_b32_e32 v5, 16, v16
	v_add3_u32 v15, v22, v18, s11
	v_add3_u32 v18, v24, v20, s11
	s_waitcnt vmcnt(4)
	v_bfe_u32 v20, v26, 16, 1
	v_bfe_u32 v22, v28, 16, 1
	v_add3_u32 v16, v23, v19, s11
	v_add3_u32 v19, v25, v21, s11
	v_bfe_u32 v21, v27, 16, 1
	v_bfe_u32 v23, v29, 16, 1
	global_store_dwordx2 v[42:43], v[2:3], off
	v_and_or_b32 v2, v14, s23, v4
	v_and_or_b32 v3, v17, s23, v5
	v_lshrrev_b32_e32 v4, 16, v15
	v_lshrrev_b32_e32 v5, 16, v18
	v_add3_u32 v14, v26, v20, s11
	v_add3_u32 v17, v28, v22, s11
	s_waitcnt vmcnt(4)
	v_bfe_u32 v20, v30, 16, 1
	v_bfe_u32 v22, v32, 16, 1
	v_add3_u32 v15, v27, v21, s11
	v_add3_u32 v18, v29, v23, s11
	v_bfe_u32 v21, v31, 16, 1
	v_bfe_u32 v23, v33, 16, 1
	global_store_dwordx2 v[44:45], v[2:3], off
	v_and_or_b32 v2, v16, s23, v4
	v_and_or_b32 v3, v19, s23, v5
	v_lshrrev_b32_e32 v4, 16, v14
	v_lshrrev_b32_e32 v5, 16, v17
	v_add3_u32 v14, v30, v20, s11
	v_add3_u32 v17, v32, v22, s11
	s_waitcnt vmcnt(4)
	v_bfe_u32 v20, v34, 16, 1
	v_bfe_u32 v22, v36, 16, 1
	v_add3_u32 v16, v31, v21, s11
	v_add3_u32 v19, v33, v23, s11
	v_bfe_u32 v21, v35, 16, 1
	v_bfe_u32 v23, v37, 16, 1
	global_store_dwordx2 v[46:47], v[2:3], off
	v_and_or_b32 v2, v15, s23, v4
	v_and_or_b32 v3, v18, s23, v5
	v_lshrrev_b32_e32 v4, 16, v14
	v_lshrrev_b32_e32 v5, 16, v17
	v_add3_u32 v14, v34, v20, s11
	v_add3_u32 v17, v36, v22, s11
	s_waitcnt vmcnt(4)
	v_bfe_u32 v20, v38, 16, 1
	v_bfe_u32 v22, v40, 16, 1
	v_add3_u32 v15, v35, v21, s11
	v_add3_u32 v18, v37, v23, s11
	v_bfe_u32 v21, v39, 16, 1
	v_bfe_u32 v23, v41, 16, 1
	global_store_dwordx2 v[48:49], v[2:3], off
	v_and_or_b32 v2, v16, s23, v4
	v_and_or_b32 v3, v19, s23, v5
	v_lshrrev_b32_e32 v4, 16, v14
	v_lshrrev_b32_e32 v5, 16, v17
	v_add3_u32 v14, v38, v20, s11
	v_add3_u32 v17, v40, v22, s11
	v_add3_u32 v16, v39, v21, s11
	v_add3_u32 v19, v41, v23, s11
	global_store_dwordx2 v[50:51], v[2:3], off
	v_and_or_b32 v2, v15, s23, v4
	v_and_or_b32 v3, v18, s23, v5
	v_lshrrev_b32_e32 v4, 16, v14
	v_lshrrev_b32_e32 v5, 16, v17
	global_store_dwordx2 v[52:53], v[2:3], off
	v_and_or_b32 v2, v16, s23, v4
	v_and_or_b32 v3, v19, s23, v5
	global_store_dwordx2 v[54:55], v[2:3], off
	s_andn2_b64 exec, exec, s[6:7]
	s_cbranch_execnz .LBB0_23

; __device__ __forceinline__ void transpose_item(const float* W, int K, int N, bf16_t* WT, int mode, LAS float* scr, int item, int lane, const float* gvec, const float* bvec, float* csp, int nblk, int nmagic) {
;     const int kb = (item * nmagic) >> 20, nb = item - kb * nblk, k0 = 64 * kb, n0 = 64 * nb;
;     int r0 = n0;
;     if (mode == 1) { const int bj = n0 / DFF, rem = n0 % DFF; r0 = 256 * (rem / 128) + 128 * bj + (rem % 128); }
;     const int rr = lane >> 4, q = lane & 15;
;     f32x4 t[16];
; #pragma unroll
;     for (int i = 0; i < 16; ++i) t[i] = *(const f32x4*)(W + (size_t)(k0 + 4 * i + rr) * N + n0 + 4 * q);
.LBB0_65:
	s_lshl_b32 s26, s0, 6
	v_add_u32_e32 v55, s26, v19
	s_ashr_i32 s3, s2, 31
	v_lshl_add_u64 v[48:49], s[2:3], 2, v[36:37]
	v_mad_u64_u32 v[2:3], s[2:3], v55, s35, 0
	s_waitcnt lgkmcnt(0)
	v_ashrrev_i32_e32 v5, 31, v55
	v_mov_b32_e32 v4, v3
	v_mad_u64_u32 v[4:5], s[2:3], v5, s35, v[4:5]
	v_add_u32_e32 v10, 8, v55
	v_mov_b32_e32 v3, v4
	v_add_u32_e32 v4, 4, v55
	v_ashrrev_i32_e32 v13, 31, v10
	v_mad_u64_u32 v[10:11], s[2:3], v10, s35, 0
	v_ashrrev_i32_e32 v7, 31, v4
	v_mad_u64_u32 v[4:5], s[2:3], v4, s35, 0
	v_mov_b32_e32 v12, v11
	v_mov_b32_e32 v6, v5
	v_mad_u64_u32 v[12:13], s[2:3], v13, s35, v[12:13]
	v_mad_u64_u32 v[6:7], s[2:3], v7, s35, v[6:7]
	v_mov_b32_e32 v11, v12
	v_add_u32_e32 v12, 12, v55
	v_add_u32_e32 v44, 16, v55
	v_mov_b32_e32 v5, v6
	v_ashrrev_i32_e32 v15, 31, v12
	v_mad_u64_u32 v[12:13], s[2:3], v12, s35, 0
	v_ashrrev_i32_e32 v47, 31, v44
	v_mad_u64_u32 v[44:45], s[2:3], v44, s35, 0
	v_lshl_add_u64 v[2:3], v[2:3], 2, v[48:49]
	v_lshl_add_u64 v[6:7], v[4:5], 2, v[48:49]
	v_mov_b32_e32 v14, v13
	v_mov_b32_e32 v46, v45
	global_load_dwordx4 v[2:5], v[2:3], off nt
	s_nop 0
	global_load_dwordx4 v[6:9], v[6:7], off nt
	v_mad_u64_u32 v[14:15], s[2:3], v15, s35, v[14:15]
	v_mad_u64_u32 v[46:47], s[2:3], v47, s35, v[46:47]
	v_mov_b32_e32 v13, v14
	v_mov_b32_e32 v45, v46
	v_add_u32_e32 v46, 20, v55
	v_add_u32_e32 v60, 24, v55
	v_lshl_add_u64 v[10:11], v[10:11], 2, v[48:49]
	v_lshl_add_u64 v[14:15], v[12:13], 2, v[48:49]
	v_ashrrev_i32_e32 v57, 31, v46
	v_mad_u64_u32 v[46:47], s[2:3], v46, s35, 0
	v_ashrrev_i32_e32 v63, 31, v60
	v_mad_u64_u32 v[60:61], s[2:3], v60, s35, 0
	global_load_dwordx4 v[10:13], v[10:11], off nt
	s_nop 0
	global_load_dwordx4 v[14:17], v[14:15], off nt
	v_mov_b32_e32 v56, v47
	v_mov_b32_e32 v62, v61
	v_mad_u64_u32 v[56:57], s[2:3], v57, s35, v[56:57]
	v_mad_u64_u32 v[62:63], s[2:3], v63, s35, v[62:63]
	v_mov_b32_e32 v47, v56
	v_mov_b32_e32 v61, v62
	v_add_u32_e32 v62, 28, v55
	v_add_u32_e32 v68, 32, v55
	v_lshl_add_u64 v[44:45], v[44:45], 2, v[48:49]
	v_lshl_add_u64 v[56:57], v[46:47], 2, v[48:49]
	v_ashrrev_i32_e32 v65, 31, v62
	v_mad_u64_u32 v[62:63], s[2:3], v62, s35, 0
	v_ashrrev_i32_e32 v71, 31, v68
	v_mad_u64_u32 v[68:69], s[2:3], v68, s35, 0
	global_load_dwordx4 v[44:47], v[44:45], off nt
	s_nop 0
	global_load_dwordx4 v[56:59], v[56:57], off nt
	v_mov_b32_e32 v64, v63
	v_mov_b32_e32 v70, v69
	v_mad_u64_u32 v[64:65], s[2:3], v65, s35, v[64:65]
	v_mad_u64_u32 v[70:71], s[2:3], v71, s35, v[70:71]
	v_mov_b32_e32 v63, v64
	v_mov_b32_e32 v69, v70
	v_add_u32_e32 v70, 36, v55
	v_add_u32_e32 v76, 40, v55
	v_lshl_add_u64 v[60:61], v[60:61], 2, v[48:49]
	v_lshl_add_u64 v[64:65], v[62:63], 2, v[48:49]
	v_ashrrev_i32_e32 v73, 31, v70
	v_mad_u64_u32 v[70:71], s[2:3], v70, s35, 0
	v_ashrrev_i32_e32 v79, 31, v76
	v_mad_u64_u32 v[76:77], s[2:3], v76, s35, 0
	global_load_dwordx4 v[60:63], v[60:61], off nt
	s_nop 0
	global_load_dwordx4 v[64:67], v[64:65], off nt
	v_mov_b32_e32 v72, v71
	v_mov_b32_e32 v78, v77
	v_mad_u64_u32 v[72:73], s[2:3], v73, s35, v[72:73]
	v_mad_u64_u32 v[78:79], s[2:3], v79, s35, v[78:79]
	v_mov_b32_e32 v71, v72
	v_mov_b32_e32 v77, v78
	v_add_u32_e32 v78, 44, v55
	v_add_u32_e32 v84, 48, v55
	v_lshl_add_u64 v[68:69], v[68:69], 2, v[48:49]
	v_lshl_add_u64 v[72:73], v[70:71], 2, v[48:49]
	v_ashrrev_i32_e32 v81, 31, v78
	v_mad_u64_u32 v[78:79], s[2:3], v78, s35, 0
	v_ashrrev_i32_e32 v87, 31, v84
	v_mad_u64_u32 v[84:85], s[2:3], v84, s35, 0
	global_load_dwordx4 v[68:71], v[68:69], off nt
	s_nop 0
	global_load_dwordx4 v[72:75], v[72:73], off nt
	v_mov_b32_e32 v80, v79
	v_mov_b32_e32 v86, v85
	v_mad_u64_u32 v[80:81], s[2:3], v81, s35, v[80:81]
	v_mad_u64_u32 v[86:87], s[2:3], v87, s35, v[86:87]
	v_mov_b32_e32 v79, v80
	v_mov_b32_e32 v85, v86
	v_add_u32_e32 v86, 52, v55
	v_lshl_add_u64 v[76:77], v[76:77], 2, v[48:49]
	v_lshl_add_u64 v[80:81], v[78:79], 2, v[48:49]
	v_ashrrev_i32_e32 v89, 31, v86
	v_mad_u64_u32 v[86:87], s[2:3], v86, s35, 0
	global_load_dwordx4 v[76:79], v[76:77], off nt
	s_nop 0
	global_load_dwordx4 v[80:83], v[80:81], off nt
	v_mov_b32_e32 v88, v87
	v_mad_u64_u32 v[88:89], s[2:3], v89, s35, v[88:89]
	v_add_u32_e32 v92, 56, v55
	v_mov_b32_e32 v87, v88
	v_ashrrev_i32_e32 v95, 31, v92
	v_mad_u64_u32 v[92:93], s[2:3], v92, s35, 0
	v_lshl_add_u64 v[84:85], v[84:85], 2, v[48:49]
	v_lshl_add_u64 v[88:89], v[86:87], 2, v[48:49]
	v_mov_b32_e32 v94, v93
	v_add_u32_e32 v55, 60, v55
	global_load_dwordx4 v[84:87], v[84:85], off
	s_nop 0
	global_load_dwordx4 v[88:91], v[88:89], off
	v_mad_u64_u32 v[94:95], s[2:3], v95, s35, v[94:95]
	v_mad_u64_u32 v[96:97], s[2:3], v55, s35, 0
	v_mov_b32_e32 v93, v94
	v_ashrrev_i32_e32 v99, 31, v55
	v_mov_b32_e32 v98, v97
	v_lshl_add_u64 v[92:93], v[92:93], 2, v[48:49]
	v_mad_u64_u32 v[98:99], s[2:3], v99, s35, v[98:99]
	global_load_dwordx4 v[92:95], v[92:93], off
	v_mov_b32_e32 v97, v98
	v_lshl_add_u64 v[48:49], v[96:97], 2, v[48:49]
	global_load_dwordx4 v[96:99], v[48:49], off
	s_waitcnt vmcnt(15)
; #define LAS __attribute__((address_space(3)))
; #define LDS_WAIT() asm volatile("s_waitcnt lgkmcnt(0)" ::: "memory")
; __device__ __forceinline__ void transpose_item(const float* W, int K, int N, bf16_t* WT, int mode, LAS float* scr, int item, int lane, const float* gvec, const float* bvec, float* csp, int nblk, int nmagic) {
;     ...
;     for (int i = 0; i < 16; ++i) { LAS float* d = scr + (4 * i + rr) * 65 + 4 * q; d[0] = t[i][0]; d[1] = t[i][1]; d[2] = t[i][2]; d[3] = t[i][3]; }
;     LDS_WAIT(); asm volatile("" ::: "memory");
;     const int c = lane & 7;
;     if (csp) {
;         f32x4 g0 = (f32x4){1.f, 1.f, 1.f, 1.f}, g1 = g0, b0 = (f32x4){0.f, 0.f, 0.f, 0.f}, b1 = b0;
;         if (gvec) { g0 = *(const f32x4*)(gvec + k0 + 8 * c); g1 = *(const f32x4*)(gvec + k0 + 8 * c + 4); b0 = *(const f32x4*)(bvec + k0 + 8 * c); b1 = *(const f32x4*)(bvec + k0 + 8 * c + 4); }
	ds_write2_b32 v54, v2, v3 offset1:1
	ds_write2_b32 v54, v4, v5 offset0:2 offset1:3
	v_add_u32_e32 v2, 0x410, v54
	s_waitcnt vmcnt(14)
	ds_write2_b32 v2, v6, v7 offset1:1
	v_add_u32_e32 v2, 0x418, v54
	ds_write2_b32 v2, v8, v9 offset1:1
	v_add_u32_e32 v2, 0x820, v54
	s_waitcnt vmcnt(13)
	ds_write2_b32 v2, v10, v11 offset1:1
	v_add_u32_e32 v2, 0x828, v54
	ds_write2_b32 v2, v12, v13 offset1:1
	v_add_u32_e32 v2, 0xc30, v54
	s_waitcnt vmcnt(12)
	ds_write2_b32 v2, v14, v15 offset1:1
	v_add_u32_e32 v2, 0xc38, v54
	ds_write2_b32 v2, v16, v17 offset1:1
	v_add_u32_e32 v2, 0x1040, v54
	s_waitcnt vmcnt(11)
	ds_write2_b32 v2, v44, v45 offset1:1
	v_add_u32_e32 v2, 0x1048, v54
	ds_write2_b32 v2, v46, v47 offset1:1
	v_add_u32_e32 v2, 0x1450, v54
	s_waitcnt vmcnt(10)
	ds_write2_b32 v2, v56, v57 offset1:1
	v_add_u32_e32 v2, 0x1458, v54
	ds_write2_b32 v2, v58, v59 offset1:1
	v_add_u32_e32 v2, 0x1860, v54
	s_waitcnt vmcnt(9)
	ds_write2_b32 v2, v60, v61 offset1:1
	v_add_u32_e32 v2, 0x1868, v54
	ds_write2_b32 v2, v62, v63 offset1:1
	v_add_u32_e32 v2, 0x1c70, v54
	s_waitcnt vmcnt(8)
	ds_write2_b32 v2, v64, v65 offset1:1
	v_add_u32_e32 v2, 0x1c78, v54
	ds_write2_b32 v2, v66, v67 offset1:1
	v_add_u32_e32 v2, 0x2080, v54
	s_ashr_i32 s27, s26, 31
	s_and_b64 vcc, exec, s[54:55]
	s_waitcnt vmcnt(7)
	ds_write2_b32 v2, v68, v69 offset1:1
	v_add_u32_e32 v2, 0x2088, v54
	ds_write2_b32 v2, v70, v71 offset1:1
	v_add_u32_e32 v2, 0x2490, v54
	s_waitcnt vmcnt(6)
	ds_write2_b32 v2, v72, v73 offset1:1
	v_add_u32_e32 v2, 0x2498, v54
	ds_write2_b32 v2, v74, v75 offset1:1
	v_add_u32_e32 v2, 0x28a0, v54
	s_waitcnt vmcnt(5)
	ds_write2_b32 v2, v76, v77 offset1:1
	v_add_u32_e32 v2, 0x28a8, v54
	ds_write2_b32 v2, v78, v79 offset1:1
	v_add_u32_e32 v2, 0x2cb0, v54
	s_waitcnt vmcnt(4)
	ds_write2_b32 v2, v80, v81 offset1:1
	v_add_u32_e32 v2, 0x2cb8, v54
	ds_write2_b32 v2, v82, v83 offset1:1
	v_add_u32_e32 v2, 0x30c0, v54
	s_waitcnt vmcnt(3)
	ds_write2_b32 v2, v84, v85 offset1:1
	v_add_u32_e32 v2, 0x30c8, v54
	ds_write2_b32 v2, v86, v87 offset1:1
	v_add_u32_e32 v2, 0x34d0, v54
	s_waitcnt vmcnt(2)
	ds_write2_b32 v2, v88, v89 offset1:1
	v_add_u32_e32 v2, 0x34d8, v54
	ds_write2_b32 v2, v90, v91 offset1:1
	v_add_u32_e32 v2, 0x38e0, v54
	s_waitcnt vmcnt(1)
	ds_write2_b32 v2, v92, v93 offset1:1
	v_add_u32_e32 v2, 0x38e8, v54
	ds_write2_b32 v2, v94, v95 offset1:1
	v_add_u32_e32 v2, 0x3cf0, v54
	s_waitcnt vmcnt(0)
	ds_write2_b32 v2, v96, v97 offset1:1
	v_add_u32_e32 v2, 0x3cf8, v54
	ds_write2_b32 v2, v98, v99 offset1:1
	s_waitcnt lgkmcnt(0)
	s_cbranch_vccz .LBB0_68
	s_andn2_b64 vcc, exec, s[56:57]
	s_cbranch_vccnz .LBB0_69
	s_lshl_b64 s[2:3], s[26:27], 2
	v_lshl_add_u64 v[2:3], v[40:41], 0, s[2:3]
	global_load_dwordx4 v[10:13], v[2:3], off offset:16
	global_load_dwordx4 v[14:17], v[2:3], off
	v_lshl_add_u64 v[6:7], v[38:39], 0, s[2:3]
	global_load_dwordx4 v[2:5], v[6:7], off offset:16
	s_nop 0
	global_load_dwordx4 v[6:9], v[6:7], off
	s_waitcnt vmcnt(3)
	v_mov_b32_e32 v44, v11
	v_mov_b32_e32 v45, v12
	v_mov_b32_e32 v11, v13
	s_waitcnt vmcnt(2)
	v_mov_b32_e32 v46, v15
	v_mov_b32_e32 v47, v16
	v_mov_b32_e32 v15, v17
	s_branch .LBB0_70

; __device__ __forceinline__ void ln_row(const float* xin, float* yout, bf16_t* ybf, const float* g, const float* b, int lane) {
;     const f32x4* xr = (const f32x4*)xin + lane;
;     f32x4 v[8]; float s = 0.f;
; #pragma unroll
;     for (int j = 0; j < 8; ++j) { v[j] = xr[64 * j]; s += (v[j][0] + v[j][1]) + (v[j][2] + v[j][3]); }
;     const float mean = wave_sum(s, lane) * (1.f / DM); float s2 = 0.f;
; #pragma unroll
;     for (int j = 0; j < 8; ++j) { v[j] = v[j] - mean; s2 += (v[j][0] * v[j][0] + v[j][1] * v[j][1]) + (v[j][2] * v[j][2] + v[j][3] * v[j][3]); }
;     const float rstd = 1.f / sqrtf(wave_sum(s2, lane) * (1.f / DM) + LN_EPS);
.LBB0_1298:
	global_load_dwordx4 v[8:11], v[52:53], off offset:-3072
	global_load_dwordx4 v[12:15], v[52:53], off offset:-2048
	global_load_dwordx4 v[4:7], v[52:53], off offset:-1024
	v_add_co_u32_e32 v54, vcc, 0xfffff000, v52
	global_load_dwordx4 v[0:3], v[52:53], off
	s_nop 0
	v_addc_co_u32_e32 v55, vcc, -1, v53, vcc
	global_load_dwordx4 v[28:31], v[54:55], off offset:-3072
	global_load_dwordx4 v[24:27], v[54:55], off offset:-2048
	global_load_dwordx4 v[20:23], v[54:55], off offset:-1024
	global_load_dwordx4 v[16:19], v[52:53], off offset:-4096
	s_addk_i32 s4, 0x800
	s_cmpk_gt_i32 s4, 0x77ff
	s_waitcnt vmcnt(7)
	v_mov_b32_e32 v67, v10
	s_waitcnt vmcnt(6)
	v_mov_b32_e32 v70, v13
	v_mov_b32_e32 v71, v14
	v_mov_b32_e32 v72, v12
	v_mov_b32_e32 v73, v15
	s_waitcnt vmcnt(5)
	v_add_f32_e32 v74, v4, v5
	v_add_f32_e32 v76, v6, v7
	s_waitcnt vmcnt(4)
	v_mov_b32_e32 v75, v2
	v_mov_b32_e32 v77, v3
	v_pk_add_f32 v[70:71], v[70:71], v[72:73]
	v_pk_add_f32 v[72:73], v[74:75], v[76:77]
	s_waitcnt vmcnt(3)
	v_mov_b32_e32 v74, v28
	s_waitcnt vmcnt(2)
	v_mov_b32_e32 v75, v24
	v_mov_b32_e32 v76, v29
	v_mov_b32_e32 v77, v25
	v_mov_b32_e32 v78, v30
	v_mov_b32_e32 v79, v26
	v_mov_b32_e32 v80, v31
	v_mov_b32_e32 v81, v27
	v_mov_b32_e32 v69, v11
	s_waitcnt vmcnt(1)
	v_mov_b32_e32 v82, v21
	v_mov_b32_e32 v83, v22
	v_mov_b32_e32 v84, v20
	v_mov_b32_e32 v85, v23
	s_waitcnt vmcnt(0)
	v_add_f32_e32 v66, v16, v17
	v_add_f32_e32 v68, v18, v19
	v_pk_add_f32 v[74:75], v[74:75], v[76:77]
	v_pk_add_f32 v[76:77], v[78:79], v[80:81]
	v_pk_add_f32 v[78:79], v[82:83], v[84:85]
	v_pk_add_f32 v[66:67], v[66:67], v[68:69]
	v_pk_add_f32 v[68:69], v[74:75], v[76:77]
	v_pk_add_f32 v[74:75], v[78:79], v[78:79] op_sel:[0,1] op_sel_hi:[1,0]
	v_add_f32_e32 v64, 0, v68
	v_mov_b32_e32 v65, v8
	v_mov_b32_e32 v75, v9
	v_add_f32_e32 v64, v64, v69
	v_pk_add_f32 v[64:65], v[64:65], v[74:75]
	v_pk_add_f32 v[70:71], v[70:71], v[70:71] op_sel:[0,1] op_sel_hi:[1,0]
	v_pk_add_f32 v[64:65], v[64:65], v[66:67]
	v_mov_b32_e32 v71, v1
	v_pk_add_f32 v[64:65], v[64:65], v[64:65] op_sel:[0,1] op_sel_hi:[1,0]
	s_nop 0
	v_mov_b32_e32 v65, v0
	v_pk_add_f32 v[64:65], v[64:65], v[70:71]
	s_nop 0
	v_pk_add_f32 v[64:65], v[64:65], v[72:73]
	s_nop 0
	v_add_f32_e32 v64, v64, v65
	ds_bpermute_b32 v65, v56, v64
	s_waitcnt lgkmcnt(0)
	v_add_f32_e32 v64, v64, v65
	ds_bpermute_b32 v65, v57, v64
	s_waitcnt lgkmcnt(0)
	v_add_f32_e32 v64, v64, v65
	ds_bpermute_b32 v65, v58, v64
	s_waitcnt lgkmcnt(0)
	v_add_f32_e32 v64, v64, v65
	ds_bpermute_b32 v65, v59, v64
	s_waitcnt lgkmcnt(0)
	v_add_f32_e32 v64, v64, v65
	ds_bpermute_b32 v65, v60, v64
	s_waitcnt lgkmcnt(0)
	v_add_f32_e32 v64, v64, v65
	ds_bpermute_b32 v65, v61, v64
	s_waitcnt lgkmcnt(0)
	v_add_f32_e32 v87, v64, v65
	v_fmamk_f32 v31, v87, 0xba000000, v31
	v_fmamk_f32 v29, v87, 0xba000000, v29
	v_fmamk_f32 v27, v87, 0xba000000, v27
	v_fmamk_f32 v25, v87, 0xba000000, v25
	v_fmamk_f32 v30, v87, 0xba000000, v30
	v_fmac_f32_e32 v28, 0xba000000, v87
	v_fmamk_f32 v26, v87, 0xba000000, v26
	v_fmac_f32_e32 v24, 0xba000000, v87
	v_fmamk_f32 v21, v87, 0xba000000, v21
	v_fmamk_f32 v20, v87, 0xba000000, v20
	v_fmamk_f32 v23, v87, 0xba000000, v23
	v_fmac_f32_e32 v22, 0xba000000, v87
	v_mov_b32_e32 v66, v29
	v_mov_b32_e32 v67, v25
	v_mov_b32_e32 v70, v31
	v_mov_b32_e32 v71, v27
	v_mov_b32_e32 v64, v28
	v_mov_b32_e32 v65, v24
	v_mov_b32_e32 v68, v30
	v_mov_b32_e32 v69, v26
	v_pk_mul_f32 v[72:73], v[22:23], v[22:23]
	v_pk_mul_f32 v[74:75], v[20:21], v[20:21]
	v_pk_mul_f32 v[66:67], v[66:67], v[66:67]
	v_pk_mul_f32 v[70:71], v[70:71], v[70:71]
	v_fmamk_f32 v16, v87, 0xba000000, v16
	v_fmac_f32_e32 v18, 0xba000000, v87
	v_pk_mov_b32 v[88:89], v[74:75], v[72:73] op_sel:[1,0]
	v_mov_b32_e32 v75, v73
	v_pk_fma_f32 v[64:65], v[64:65], v[64:65], v[66:67]
	v_pk_fma_f32 v[66:67], v[68:69], v[68:69], v[70:71]
	v_fmamk_f32 v17, v87, 0xba000000, v17
	v_fmamk_f32 v19, v87, 0xba000000, v19
	v_mul_f32_e32 v76, v16, v16
	v_mul_f32_e32 v78, v18, v18
	v_pk_add_f32 v[68:69], v[88:89], v[74:75]
	v_pk_add_f32 v[64:65], v[64:65], v[66:67]
	v_fmamk_f32 v11, v87, 0xba000000, v11
	v_fmamk_f32 v10, v87, 0xba000000, v10
	v_fmamk_f32 v9, v87, 0xba000000, v9
	v_fmac_f32_e32 v8, 0xba000000, v87
	v_fmamk_f32 v13, v87, 0xba000000, v13
	v_fmamk_f32 v12, v87, 0xba000000, v12
	v_fmamk_f32 v15, v87, 0xba000000, v15
	v_fmac_f32_e32 v14, 0xba000000, v87
	v_pk_fma_f32 v[72:73], v[16:17], v[16:17], v[76:77] op_sel_hi:[1,1,0]
	v_pk_fma_f32 v[76:77], v[18:19], v[18:19], v[78:79] op_sel_hi:[1,1,0]
	v_pk_add_f32 v[66:67], v[68:69], v[68:69] op_sel_hi:[0,1]
	v_pk_add_f32 v[64:65], v[64:65], v[64:65] op_sel_hi:[0,1]
	v_pk_mul_f32 v[80:81], v[14:15], v[14:15]
	v_pk_mul_f32 v[82:83], v[12:13], v[12:13]
	v_mul_f32_e32 v72, v8, v8
	v_mul_f32_e32 v76, v9, v9
	v_mul_f32_e32 v66, v10, v10
	v_mul_f32_e32 v64, v11, v11
	v_pk_mov_b32 v[78:79], v[82:83], v[80:81] op_sel:[1,0]
	v_mov_b32_e32 v83, v81
	v_pk_add_f32 v[68:69], v[72:73], v[76:77]
	v_pk_add_f32 v[64:65], v[66:67], v[64:65]
	v_pk_add_f32 v[70:71], v[78:79], v[82:83]
	v_pk_add_f32 v[64:65], v[68:69], v[64:65]
	v_pk_add_f32 v[72:73], v[70:71], v[70:71] op_sel_hi:[0,1]
	v_pk_add_f32 v[74:75], v[64:65], v[64:65] op_sel_hi:[0,1]
	v_fmamk_f32 v4, v87, 0xba000000, v4
	v_fmac_f32_e32 v6, 0xba000000, v87
	v_fmamk_f32 v5, v87, 0xba000000, v5
	v_fmamk_f32 v7, v87, 0xba000000, v7
	v_mul_f32_e32 v84, v4, v4
	v_mul_f32_e32 v86, v6, v6
	v_pk_fma_f32 v[80:81], v[4:5], v[4:5], v[84:85] op_sel_hi:[1, 1, 0]
	v_pk_fma_f32 v[84:85], v[6:7], v[6:7], v[86:87] op_sel_hi:[1, 1, 0]
	v_fmamk_f32 v77, v87, 0xba000000, v3
	v_fmamk_f32 v76, v87, 0xba000000, v2
	v_fmamk_f32 v1, v87, 0xba000000, v1
	v_fmac_f32_e32 v0, 0xba000000, v87
	v_mul_f32_e32 v80, v0, v0
	v_mul_f32_e32 v84, v1, v1
	v_mul_f32_e32 v72, v76, v76
	v_mul_f32_e32 v74, v77, v77
	v_pk_add_f32 v[2:3], v[80:81], v[84:85]
	v_pk_add_f32 v[72:73], v[72:73], v[74:75]
	s_nop 0
	v_pk_add_f32 v[2:3], v[2:3], v[72:73]
	s_nop 0
	v_add_f32_e32 v2, v2, v3
	ds_bpermute_b32 v3, v56, v2
	s_waitcnt lgkmcnt(0)
; __device__ __forceinline__ unsigned pk2(float lo, float hi) { return f2bf(lo) | (f2bf(hi) << 16); }
; __device__ __forceinline__ void ln_row(const float* xin, float* yout, bf16_t* ybf, const float* g, const float* b, int lane) {
;     ...
;     const float rstd = 1.f / sqrtf(wave_sum(s2, lane) * (1.f / DM) + LN_EPS);
;     f32x4* yo = (f32x4*)yout + lane; u32x2* o8 = (u32x2*)ybf + lane;
; #pragma unroll
;     for (int j = 0; j < 8; ++j) { const f32x4 gg = ((const f32x4*)g)[lane + 64 * j], bb = ((const f32x4*)b)[lane + 64 * j];
;         const f32x4 y = v[j] * rstd * gg + bb; yo[64 * j] = y; if (ybf) { u32x2 w; w.x = pk2(y[0], y[1]); w.y = pk2(y[2], y[3]); o8[64 * j] = w; } }
	v_add_f32_e32 v2, v2, v3
	ds_bpermute_b32 v3, v57, v2
	s_waitcnt lgkmcnt(0)
	v_add_f32_e32 v2, v2, v3
	ds_bpermute_b32 v3, v58, v2
	s_waitcnt lgkmcnt(0)
	v_add_f32_e32 v2, v2, v3
	ds_bpermute_b32 v3, v59, v2
	s_waitcnt lgkmcnt(0)
	v_add_f32_e32 v2, v2, v3
	ds_bpermute_b32 v3, v60, v2
	s_waitcnt lgkmcnt(0)
	v_add_f32_e32 v2, v2, v3
	ds_bpermute_b32 v3, v61, v2
	s_waitcnt lgkmcnt(0)
	v_add_f32_e32 v2, v2, v3
	v_fmamk_f32 v2, v2, 0x3a000000, v62
	v_mul_f32_e32 v3, 0x4f800000, v2
	v_cmp_gt_f32_e32 vcc, s5, v2
	s_nop 1
	v_cndmask_b32_e32 v2, v2, v3, vcc
	v_sqrt_f32_e32 v3, v2
	s_nop 0
	v_add_u32_e32 v72, -1, v3
	v_add_u32_e32 v73, 1, v3
	v_fma_f32 v74, -v72, v3, v2
	v_fma_f32 v75, -v73, v3, v2
	v_cmp_ge_f32_e64 s[0:1], 0, v74
	s_nop 1
	v_cndmask_b32_e64 v3, v3, v72, s[0:1]
	v_cmp_lt_f32_e64 s[0:1], 0, v75
	s_nop 1
	v_cndmask_b32_e64 v3, v3, v73, s[0:1]
	v_mul_f32_e32 v72, 0x37800000, v3
	v_cndmask_b32_e32 v3, v3, v72, vcc
	v_cmp_class_f32_e32 vcc, v2, v63
	s_nop 1
	v_cndmask_b32_e32 v2, v3, v2, vcc
	v_div_scale_f32 v3, s[0:1], v2, v2, 1.0
	v_rcp_f32_e32 v72, v3
	v_div_scale_f32 v73, vcc, 1.0, v2, 1.0
	v_fma_f32 v74, -v3, v72, 1.0
	v_fmac_f32_e32 v72, v74, v72
	v_mul_f32_e32 v74, v73, v72
	v_fma_f32 v75, -v3, v74, v73
	v_fmac_f32_e32 v74, v75, v72
	v_fma_f32 v3, -v3, v74, v73
	v_div_fmas_f32 v3, v3, v72, v74
	v_div_fixup_f32 v72, v3, v2, 1.0
	v_pk_mul_f32 v[2:3], v[28:29], v[72:73] op_sel_hi:[1, 0]
	v_pk_mul_f32 v[28:29], v[30:31], v[72:73] op_sel_hi:[1, 0]
	v_pk_mul_f32 v[24:25], v[24:25], v[72:73] op_sel_hi:[1, 0]
	v_pk_fma_f32 v[30:31], v[102:103], v[28:29], v[134:135]
	v_pk_fma_f32 v[28:29], v[100:101], v[2:3], v[132:133]
	global_store_dwordx4 v[54:55], v[28:31], off offset:-3072 nt
	s_nop 1
	s_nop 0
	v_pk_mul_f32 v[2:3], v[26:27], v[72:73] op_sel_hi:[1, 0]
	v_pk_mul_f32 v[20:21], v[20:21], v[72:73] op_sel_hi:[1, 0]
	v_pk_mul_f32 v[16:17], v[16:17], v[72:73] op_sel_hi:[1, 0]
	v_pk_mul_f32 v[8:9], v[8:9], v[72:73] op_sel_hi:[1, 0]
	v_pk_mul_f32 v[12:13], v[12:13], v[72:73] op_sel_hi:[1, 0]
	v_pk_mul_f32 v[6:7], v[6:7], v[72:73] op_sel_hi:[1, 0]
	v_pk_mul_f32 v[0:1], v[0:1], v[72:73] op_sel_hi:[1, 0]
	v_pk_fma_f32 v[24:25], v[104:105], v[24:25], v[136:137]
	v_pk_fma_f32 v[26:27], v[106:107], v[2:3], v[138:139]
	global_store_dwordx4 v[54:55], v[24:27], off offset:-2048 nt
	s_nop 1
	s_nop 0
	v_pk_mul_f32 v[2:3], v[22:23], v[72:73] op_sel_hi:[1, 0]
	v_pk_fma_f32 v[20:21], v[108:109], v[20:21], v[140:141]
	v_pk_fma_f32 v[22:23], v[110:111], v[2:3], v[142:143]
	global_store_dwordx4 v[54:55], v[20:23], off offset:-1024 nt
	s_nop 1
	s_nop 0
	v_pk_mul_f32 v[2:3], v[18:19], v[72:73] op_sel_hi:[1, 0]
	v_pk_fma_f32 v[16:17], v[112:113], v[16:17], v[144:145]
	v_pk_fma_f32 v[18:19], v[114:115], v[2:3], v[146:147]
	global_store_dwordx4 v[52:53], v[16:19], off offset:-4096 nt
	s_nop 1
	s_nop 0
	v_pk_mul_f32 v[2:3], v[10:11], v[72:73] op_sel_hi:[1, 0]
	v_pk_fma_f32 v[8:9], v[116:117], v[8:9], v[148:149]
	v_pk_fma_f32 v[10:11], v[118:119], v[2:3], v[150:151]
	global_store_dwordx4 v[52:53], v[8:11], off offset:-3072 nt
	s_nop 1
	s_nop 0
	v_pk_mul_f32 v[2:3], v[14:15], v[72:73] op_sel_hi:[1, 0]
	v_pk_fma_f32 v[8:9], v[120:121], v[12:13], v[152:153]
	v_pk_fma_f32 v[10:11], v[122:123], v[2:3], v[154:155]
	global_store_dwordx4 v[52:53], v[8:11], off offset:-2048 nt
	s_nop 1
	s_nop 0
	v_pk_mul_f32 v[2:3], v[4:5], v[72:73] op_sel_hi:[1, 0]
	v_pk_fma_f32 v[4:5], v[126:127], v[6:7], v[158:159]
	v_pk_fma_f32 v[2:3], v[124:125], v[2:3], v[156:157]
	global_store_dwordx4 v[52:53], v[2:5], off offset:-1024 nt
	s_nop 1
	s_nop 0
	v_pk_mul_f32 v[10:11], v[76:77], v[72:73] op_sel_hi:[1, 0]
	v_pk_fma_f32 v[0:1], v[128:129], v[0:1], v[160:161]
	v_pk_fma_f32 v[2:3], v[130:131], v[10:11], v[162:163]
	global_store_dwordx4 v[52:53], v[0:3], off nt
	s_nop 1
	v_lshl_add_u64 v[52:53], v[52:53], 0, s[2:3]
	s_cbranch_scc0 .LBB0_1298
